# v67 + GEMM accumulator zeroing per tile with 63 v_mov_b64 instead of 126 v_mov_b32 (microbenchmark showed v_mov_b64 issues at v_mov_b32 cost)
# baseline (speedup 1.0000x reference)
.LBB0_645:
	s_ashr_i32 s23, s22, 31
	s_lshl_b64 s[24:25], s[22:23], 11
	s_add_u32 s24, s88, s24
	s_addc_u32 s25, s89, s25
	s_and_b64 s[26:27], s[2:3], exec
	s_cselect_b32 s23, s25, s29
	s_cselect_b32 s64, s24, s28
	s_ashr_i32 s21, s20, 31
	s_lshl_b64 s[26:27], s[20:21], 19
	s_add_u32 s26, s33, s26
	s_addc_u32 s27, s40, s27
	s_and_b64 s[34:35], s[2:3], exec
	s_cselect_b32 s21, s27, s31
	s_cselect_b32 s65, s26, s30
	s_add_u32 s66, s64, 0x80
	s_addc_u32 s67, s23, 0
	s_add_u32 s68, s30, 0x100
	v_mov_b32_e32 v0, 0
	s_addc_u32 s69, s31, 0
	s_mov_b32 s70, -2
	s_mov_b64 s[30:31], 0
	v_mov_b32_e32 v1, v0
	v_mov_b64_e32 v[2:3], v[0:1]
	v_mov_b64_e32 v[4:5], v[0:1]
	v_mov_b64_e32 v[6:7], v[0:1]
	v_mov_b64_e32 v[8:9], v[0:1]
	v_mov_b64_e32 v[10:11], v[0:1]
	v_mov_b64_e32 v[16:17], v[0:1]
	v_mov_b64_e32 v[18:19], v[0:1]
	v_mov_b64_e32 v[24:25], v[0:1]
	v_mov_b64_e32 v[26:27], v[0:1]
	v_mov_b64_e32 v[32:33], v[0:1]
	v_mov_b64_e32 v[34:35], v[0:1]
	v_mov_b64_e32 v[40:41], v[0:1]
	v_mov_b64_e32 v[42:43], v[0:1]
	v_mov_b64_e32 v[48:49], v[0:1]
	v_mov_b64_e32 v[50:51], v[0:1]
	v_mov_b64_e32 v[12:13], v[0:1]
	v_mov_b64_e32 v[14:15], v[0:1]
	v_mov_b64_e32 v[20:21], v[0:1]
	v_mov_b64_e32 v[22:23], v[0:1]
	v_mov_b64_e32 v[28:29], v[0:1]
	v_mov_b64_e32 v[30:31], v[0:1]
	v_mov_b64_e32 v[36:37], v[0:1]
	v_mov_b64_e32 v[38:39], v[0:1]
	v_mov_b64_e32 v[44:45], v[0:1]
	v_mov_b64_e32 v[46:47], v[0:1]
	v_mov_b64_e32 v[52:53], v[0:1]
	v_mov_b64_e32 v[54:55], v[0:1]
	v_mov_b64_e32 v[56:57], v[0:1]
	v_mov_b64_e32 v[58:59], v[0:1]
	v_mov_b64_e32 v[60:61], v[0:1]
	v_mov_b64_e32 v[62:63], v[0:1]
	v_mov_b64_e32 v[64:65], v[0:1]
	v_mov_b64_e32 v[66:67], v[0:1]
	v_mov_b64_e32 v[68:69], v[0:1]
	v_mov_b64_e32 v[70:71], v[0:1]
	v_mov_b64_e32 v[72:73], v[0:1]
	v_mov_b64_e32 v[74:75], v[0:1]
	v_mov_b64_e32 v[80:81], v[0:1]
	v_mov_b64_e32 v[82:83], v[0:1]
	v_mov_b64_e32 v[88:89], v[0:1]
	v_mov_b64_e32 v[90:91], v[0:1]
	v_mov_b64_e32 v[92:93], v[0:1]
	v_mov_b64_e32 v[94:95], v[0:1]
	v_mov_b64_e32 v[104:105], v[0:1]
	v_mov_b64_e32 v[106:107], v[0:1]
	v_mov_b64_e32 v[108:109], v[0:1]
	v_mov_b64_e32 v[110:111], v[0:1]
	v_mov_b64_e32 v[76:77], v[0:1]
	v_mov_b64_e32 v[78:79], v[0:1]
	v_mov_b64_e32 v[84:85], v[0:1]
	v_mov_b64_e32 v[86:87], v[0:1]
	v_mov_b64_e32 v[96:97], v[0:1]
	v_mov_b64_e32 v[98:99], v[0:1]
	v_mov_b64_e32 v[100:101], v[0:1]
	v_mov_b64_e32 v[102:103], v[0:1]
	v_mov_b64_e32 v[112:113], v[0:1]
	v_mov_b64_e32 v[114:115], v[0:1]
	v_mov_b64_e32 v[116:117], v[0:1]
	v_mov_b64_e32 v[118:119], v[0:1]
	v_mov_b64_e32 v[120:121], v[0:1]
	v_mov_b64_e32 v[122:123], v[0:1]
	v_mov_b64_e32 v[124:125], v[0:1]
	v_mov_b64_e32 v[126:127], v[0:1]
	v_lshl_add_u64 v[144:145], s[28:29], 0, v[136:137]
	v_lshl_add_u64 v[146:147], s[28:29], 0, v[138:139]

.LBB0_1040:
	s_ashr_i32 s15, s14, 31
	s_lshl_b64 s[16:17], s[14:15], 11
	s_add_u32 s16, s33, s16
	s_addc_u32 s17, s34, s17
	s_and_b64 s[18:19], s[4:5], exec
	s_cselect_b32 s15, s17, s23
	s_cselect_b32 s21, s16, s22
	s_ashr_i32 s13, s12, 31
	s_lshl_b64 s[18:19], s[12:13], 19
	s_add_u32 s18, s35, s18
	s_addc_u32 s19, s36, s19
	s_and_b64 s[26:27], s[4:5], exec
	s_cselect_b32 s13, s19, s25
	s_cselect_b32 s52, s18, s24
	s_add_u32 s53, s21, 0x80
	s_addc_u32 s54, s15, 0
	s_add_u32 s55, s24, 0x100
	v_mov_b32_e32 v0, 0
	s_addc_u32 s56, s25, 0
	v_lshl_add_u64 v[128:129], s[22:23], 0, v[182:183]
	v_lshl_add_u64 v[130:131], s[22:23], 0, v[184:185]
	s_mov_b32 s57, -2
	s_mov_b64 s[24:25], 0
	s_waitcnt lgkmcnt(0)
	v_mov_b32_e32 v1, v0
	v_mov_b64_e32 v[2:3], v[0:1]
	v_mov_b64_e32 v[4:5], v[0:1]
	v_mov_b64_e32 v[6:7], v[0:1]
	v_mov_b64_e32 v[16:17], v[0:1]
	v_mov_b64_e32 v[18:19], v[0:1]
	v_mov_b64_e32 v[20:21], v[0:1]
	v_mov_b64_e32 v[22:23], v[0:1]
	v_mov_b64_e32 v[32:33], v[0:1]
	v_mov_b64_e32 v[34:35], v[0:1]
	v_mov_b64_e32 v[36:37], v[0:1]
	v_mov_b64_e32 v[38:39], v[0:1]
	v_mov_b64_e32 v[48:49], v[0:1]
	v_mov_b64_e32 v[50:51], v[0:1]
	v_mov_b64_e32 v[52:53], v[0:1]
	v_mov_b64_e32 v[54:55], v[0:1]
	v_mov_b64_e32 v[8:9], v[0:1]
	v_mov_b64_e32 v[10:11], v[0:1]
	v_mov_b64_e32 v[12:13], v[0:1]
	v_mov_b64_e32 v[14:15], v[0:1]
	v_mov_b64_e32 v[24:25], v[0:1]
	v_mov_b64_e32 v[26:27], v[0:1]
	v_mov_b64_e32 v[28:29], v[0:1]
	v_mov_b64_e32 v[30:31], v[0:1]
	v_mov_b64_e32 v[40:41], v[0:1]
	v_mov_b64_e32 v[42:43], v[0:1]
	v_mov_b64_e32 v[44:45], v[0:1]
	v_mov_b64_e32 v[46:47], v[0:1]
	v_mov_b64_e32 v[56:57], v[0:1]
	v_mov_b64_e32 v[58:59], v[0:1]
	v_mov_b64_e32 v[60:61], v[0:1]
	v_mov_b64_e32 v[62:63], v[0:1]
	v_mov_b64_e32 v[64:65], v[0:1]
	v_mov_b64_e32 v[66:67], v[0:1]
	v_mov_b64_e32 v[68:69], v[0:1]
	v_mov_b64_e32 v[70:71], v[0:1]
	v_mov_b64_e32 v[80:81], v[0:1]
	v_mov_b64_e32 v[82:83], v[0:1]
	v_mov_b64_e32 v[84:85], v[0:1]
	v_mov_b64_e32 v[86:87], v[0:1]
	v_mov_b64_e32 v[96:97], v[0:1]
	v_mov_b64_e32 v[98:99], v[0:1]
	v_mov_b64_e32 v[100:101], v[0:1]
	v_mov_b64_e32 v[102:103], v[0:1]
	v_mov_b64_e32 v[112:113], v[0:1]
	v_mov_b64_e32 v[114:115], v[0:1]
	v_mov_b64_e32 v[116:117], v[0:1]
	v_mov_b64_e32 v[118:119], v[0:1]
	v_mov_b64_e32 v[72:73], v[0:1]
	v_mov_b64_e32 v[74:75], v[0:1]
	v_mov_b64_e32 v[76:77], v[0:1]
	v_mov_b64_e32 v[78:79], v[0:1]
	v_mov_b64_e32 v[88:89], v[0:1]
	v_mov_b64_e32 v[90:91], v[0:1]
	v_mov_b64_e32 v[92:93], v[0:1]
	v_mov_b64_e32 v[94:95], v[0:1]
	v_mov_b64_e32 v[104:105], v[0:1]
	v_mov_b64_e32 v[106:107], v[0:1]
	v_mov_b64_e32 v[108:109], v[0:1]
	v_mov_b64_e32 v[110:111], v[0:1]
	v_mov_b64_e32 v[120:121], v[0:1]
	v_mov_b64_e32 v[122:123], v[0:1]
	v_mov_b64_e32 v[124:125], v[0:1]
	v_mov_b64_e32 v[126:127], v[0:1]

.LBB0_1129:
	s_ashr_i32 s57, s56, 31
	s_lshl_b64 s[16:17], s[56:57], 11
	s_add_u32 s60, s88, s16
	s_addc_u32 s61, s89, s17
	s_and_b64 s[16:17], s[58:59], exec
	s_cselect_b32 s13, s61, s1
	s_cselect_b32 s23, s60, s0
	s_ashr_i32 s55, s54, 31
	s_lshl_b64 s[16:17], s[54:55], 19
	s_add_u32 s62, s66, s16
	s_addc_u32 s63, s67, s17
	s_and_b64 s[16:17], s[58:59], exec
	s_cselect_b32 s24, s63, s15
	s_cselect_b32 s25, s62, s14
	s_add_u32 s26, s23, 0x80
	s_addc_u32 s27, s13, 0
	s_add_u32 s33, s14, 0x100
	v_mov_b32_e32 v40, 0
	v_lshl_add_u64 v[100:101], s[0:1], 0, v[188:189]
	v_lshl_add_u64 v[102:103], s[0:1], 0, v[190:191]
	s_addc_u32 s55, s15, 0
	s_mov_b32 s57, -2
	s_mov_b64 s[14:15], 0
	v_mov_b32_e32 v41, v40
	v_mov_b64_e32 v[42:43], v[40:41]
	v_mov_b64_e32 v[72:73], v[40:41]
	v_mov_b64_e32 v[74:75], v[40:41]
	v_mov_b64_e32 v[0:1], v[40:41]
	v_mov_b64_e32 v[2:3], v[40:41]
	v_mov_b64_e32 v[56:57], v[40:41]
	v_mov_b64_e32 v[58:59], v[40:41]
	v_mov_b64_e32 v[8:9], v[40:41]
	v_mov_b64_e32 v[10:11], v[40:41]
	v_mov_b64_e32 v[64:65], v[40:41]
	v_mov_b64_e32 v[66:67], v[40:41]
	v_mov_b64_e32 v[16:17], v[40:41]
	v_mov_b64_e32 v[18:19], v[40:41]
	v_mov_b64_e32 v[80:81], v[40:41]
	v_mov_b64_e32 v[82:83], v[40:41]
	v_mov_b64_e32 v[44:45], v[40:41]
	v_mov_b64_e32 v[46:47], v[40:41]
	v_mov_b64_e32 v[76:77], v[40:41]
	v_mov_b64_e32 v[78:79], v[40:41]
	v_mov_b64_e32 v[4:5], v[40:41]
	v_mov_b64_e32 v[6:7], v[40:41]
	v_mov_b64_e32 v[60:61], v[40:41]
	v_mov_b64_e32 v[62:63], v[40:41]
	v_mov_b64_e32 v[12:13], v[40:41]
	v_mov_b64_e32 v[14:15], v[40:41]
	v_mov_b64_e32 v[68:69], v[40:41]
	v_mov_b64_e32 v[70:71], v[40:41]
	v_mov_b64_e32 v[20:21], v[40:41]
	v_mov_b64_e32 v[22:23], v[40:41]
	v_mov_b64_e32 v[84:85], v[40:41]
	v_mov_b64_e32 v[86:87], v[40:41]
	v_mov_b64_e32 v[112:113], v[40:41]
	v_mov_b64_e32 v[114:115], v[40:41]
	v_mov_b64_e32 v[116:117], v[40:41]
	v_mov_b64_e32 v[118:119], v[40:41]
	v_mov_b64_e32 v[24:25], v[40:41]
	v_mov_b64_e32 v[26:27], v[40:41]
	v_mov_b64_e32 v[88:89], v[40:41]
	v_mov_b64_e32 v[90:91], v[40:41]
	v_mov_b64_e32 v[32:33], v[40:41]
	v_mov_b64_e32 v[34:35], v[40:41]
	v_mov_b64_e32 v[96:97], v[40:41]
	v_mov_b64_e32 v[98:99], v[40:41]
	v_mov_b64_e32 v[48:49], v[40:41]
	v_mov_b64_e32 v[50:51], v[40:41]
	v_mov_b64_e32 v[132:133], v[40:41]
	v_mov_b64_e32 v[134:135], v[40:41]
	v_mov_b64_e32 v[120:121], v[40:41]
	v_mov_b64_e32 v[122:123], v[40:41]
	v_mov_b64_e32 v[124:125], v[40:41]
	v_mov_b64_e32 v[126:127], v[40:41]
	v_mov_b64_e32 v[28:29], v[40:41]
	v_mov_b64_e32 v[30:31], v[40:41]
	v_mov_b64_e32 v[92:93], v[40:41]
	v_mov_b64_e32 v[94:95], v[40:41]
	v_mov_b64_e32 v[36:37], v[40:41]
	v_mov_b64_e32 v[38:39], v[40:41]
	v_mov_b64_e32 v[108:109], v[40:41]
	v_mov_b64_e32 v[110:111], v[40:41]
	v_mov_b64_e32 v[52:53], v[40:41]
	v_mov_b64_e32 v[54:55], v[40:41]
	v_mov_b64_e32 v[148:149], v[40:41]
	v_mov_b64_e32 v[150:151], v[40:41]

.LBB0_1294:
	s_add_u32 s51, s6, 0x80
	s_addc_u32 s52, s7, 0
	s_add_u32 s53, s20, 0x100
	v_mov_b32_e32 v0, 0
	s_addc_u32 s54, s21, 0
	v_lshl_add_u64 v[128:129], s[18:19], 0, v[182:183]
	v_lshl_add_u64 v[130:131], s[18:19], 0, v[184:185]
	s_mov_b32 s55, -2
	s_mov_b64 s[20:21], 0
	s_waitcnt lgkmcnt(0)
	v_mov_b32_e32 v1, v0
	v_mov_b64_e32 v[2:3], v[0:1]
	v_mov_b64_e32 v[4:5], v[0:1]
	v_mov_b64_e32 v[6:7], v[0:1]
	v_mov_b64_e32 v[16:17], v[0:1]
	v_mov_b64_e32 v[18:19], v[0:1]
	v_mov_b64_e32 v[20:21], v[0:1]
	v_mov_b64_e32 v[22:23], v[0:1]
	v_mov_b64_e32 v[32:33], v[0:1]
	v_mov_b64_e32 v[34:35], v[0:1]
	v_mov_b64_e32 v[36:37], v[0:1]
	v_mov_b64_e32 v[38:39], v[0:1]
	v_mov_b64_e32 v[48:49], v[0:1]
	v_mov_b64_e32 v[50:51], v[0:1]
	v_mov_b64_e32 v[52:53], v[0:1]
	v_mov_b64_e32 v[54:55], v[0:1]
	v_mov_b64_e32 v[8:9], v[0:1]
	v_mov_b64_e32 v[10:11], v[0:1]
	v_mov_b64_e32 v[12:13], v[0:1]
	v_mov_b64_e32 v[14:15], v[0:1]
	v_mov_b64_e32 v[24:25], v[0:1]
	v_mov_b64_e32 v[26:27], v[0:1]
	v_mov_b64_e32 v[28:29], v[0:1]
	v_mov_b64_e32 v[30:31], v[0:1]
	v_mov_b64_e32 v[40:41], v[0:1]
	v_mov_b64_e32 v[42:43], v[0:1]
	v_mov_b64_e32 v[44:45], v[0:1]
	v_mov_b64_e32 v[46:47], v[0:1]
	v_mov_b64_e32 v[56:57], v[0:1]
	v_mov_b64_e32 v[58:59], v[0:1]
	v_mov_b64_e32 v[60:61], v[0:1]
	v_mov_b64_e32 v[62:63], v[0:1]
	v_mov_b64_e32 v[64:65], v[0:1]
	v_mov_b64_e32 v[66:67], v[0:1]
	v_mov_b64_e32 v[68:69], v[0:1]
	v_mov_b64_e32 v[70:71], v[0:1]
	v_mov_b64_e32 v[80:81], v[0:1]
	v_mov_b64_e32 v[82:83], v[0:1]
	v_mov_b64_e32 v[84:85], v[0:1]
	v_mov_b64_e32 v[86:87], v[0:1]
	v_mov_b64_e32 v[96:97], v[0:1]
	v_mov_b64_e32 v[98:99], v[0:1]
	v_mov_b64_e32 v[100:101], v[0:1]
	v_mov_b64_e32 v[102:103], v[0:1]
	v_mov_b64_e32 v[112:113], v[0:1]
	v_mov_b64_e32 v[114:115], v[0:1]
	v_mov_b64_e32 v[116:117], v[0:1]
	v_mov_b64_e32 v[118:119], v[0:1]
	v_mov_b64_e32 v[72:73], v[0:1]
	v_mov_b64_e32 v[74:75], v[0:1]
	v_mov_b64_e32 v[76:77], v[0:1]
	v_mov_b64_e32 v[78:79], v[0:1]
	v_mov_b64_e32 v[88:89], v[0:1]
	v_mov_b64_e32 v[90:91], v[0:1]
	v_mov_b64_e32 v[92:93], v[0:1]
	v_mov_b64_e32 v[94:95], v[0:1]
	v_mov_b64_e32 v[104:105], v[0:1]
	v_mov_b64_e32 v[106:107], v[0:1]
	v_mov_b64_e32 v[108:109], v[0:1]
	v_mov_b64_e32 v[110:111], v[0:1]
	v_mov_b64_e32 v[120:121], v[0:1]
	v_mov_b64_e32 v[122:123], v[0:1]
	v_mov_b64_e32 v[124:125], v[0:1]
	v_mov_b64_e32 v[126:127], v[0:1]

.LBB0_1383:
	s_ashr_i32 s37, s36, 31
	s_lshl_b64 s[10:11], s[36:37], 11
	s_add_u32 s38, s88, s10
	s_addc_u32 s39, s89, s11
	s_and_b64 s[10:11], s[4:5], exec
	s_cselect_b32 s7, s39, s1
	s_cselect_b32 s37, s38, s0
	s_ashr_i32 s35, s34, 31
	s_lshl_b64 s[10:11], s[34:35], 19
	s_add_u32 s40, s46, s10
	s_addc_u32 s41, s47, s11
	s_and_b64 s[10:11], s[4:5], exec
	s_cselect_b32 s35, s41, s9
	s_cselect_b32 s66, s40, s8
	s_add_u32 s67, s37, 0x80
	s_addc_u32 s68, s7, 0
	s_add_u32 s69, s8, 0x100
	v_mov_b32_e32 v0, 0
	s_waitcnt vmcnt(0)
	v_lshl_add_u64 v[64:65], s[0:1], 0, v[174:175]
	v_lshl_add_u64 v[66:67], s[0:1], 0, v[178:179]
	s_addc_u32 s70, s9, 0
	s_mov_b32 s71, -2
	s_mov_b64 s[8:9], 0
	s_waitcnt lgkmcnt(0)
	v_mov_b32_e32 v1, v0
	v_mov_b64_e32 v[2:3], v[0:1]
	v_mov_b64_e32 v[4:5], v[0:1]
	v_mov_b64_e32 v[6:7], v[0:1]
	v_mov_b64_e32 v[16:17], v[0:1]
	v_mov_b64_e32 v[18:19], v[0:1]
	v_mov_b64_e32 v[20:21], v[0:1]
	v_mov_b64_e32 v[22:23], v[0:1]
	v_mov_b64_e32 v[32:33], v[0:1]
	v_mov_b64_e32 v[34:35], v[0:1]
	v_mov_b64_e32 v[36:37], v[0:1]
	v_mov_b64_e32 v[38:39], v[0:1]
	v_mov_b64_e32 v[48:49], v[0:1]
	v_mov_b64_e32 v[50:51], v[0:1]
	v_mov_b64_e32 v[52:53], v[0:1]
	v_mov_b64_e32 v[54:55], v[0:1]
	v_mov_b64_e32 v[8:9], v[0:1]
	v_mov_b64_e32 v[10:11], v[0:1]
	v_mov_b64_e32 v[12:13], v[0:1]
	v_mov_b64_e32 v[14:15], v[0:1]
	v_mov_b64_e32 v[24:25], v[0:1]
	v_mov_b64_e32 v[26:27], v[0:1]
	v_mov_b64_e32 v[28:29], v[0:1]
	v_mov_b64_e32 v[30:31], v[0:1]
	v_mov_b64_e32 v[40:41], v[0:1]
	v_mov_b64_e32 v[42:43], v[0:1]
	v_mov_b64_e32 v[44:45], v[0:1]
	v_mov_b64_e32 v[46:47], v[0:1]
	v_mov_b64_e32 v[56:57], v[0:1]
	v_mov_b64_e32 v[58:59], v[0:1]
	v_mov_b64_e32 v[60:61], v[0:1]
	v_mov_b64_e32 v[62:63], v[0:1]
	v_mov_b64_e32 v[68:69], v[0:1]
	v_mov_b64_e32 v[70:71], v[0:1]
	v_mov_b64_e32 v[72:73], v[0:1]
	v_mov_b64_e32 v[74:75], v[0:1]
	v_mov_b64_e32 v[96:97], v[0:1]
	v_mov_b64_e32 v[98:99], v[0:1]
	v_mov_b64_e32 v[100:101], v[0:1]
	v_mov_b64_e32 v[102:103], v[0:1]
	v_mov_b64_e32 v[120:121], v[0:1]
	v_mov_b64_e32 v[122:123], v[0:1]
	v_mov_b64_e32 v[124:125], v[0:1]
	v_mov_b64_e32 v[126:127], v[0:1]
	v_mov_b64_e32 v[144:145], v[0:1]
	v_mov_b64_e32 v[146:147], v[0:1]
	v_mov_b64_e32 v[148:149], v[0:1]
	v_mov_b64_e32 v[150:151], v[0:1]
	v_mov_b64_e32 v[80:81], v[0:1]
	v_mov_b64_e32 v[82:83], v[0:1]
	v_mov_b64_e32 v[84:85], v[0:1]
	v_mov_b64_e32 v[86:87], v[0:1]
	v_mov_b64_e32 v[104:105], v[0:1]
	v_mov_b64_e32 v[106:107], v[0:1]
	v_mov_b64_e32 v[108:109], v[0:1]
	v_mov_b64_e32 v[110:111], v[0:1]
	v_mov_b64_e32 v[128:129], v[0:1]
	v_mov_b64_e32 v[130:131], v[0:1]
	v_mov_b64_e32 v[132:133], v[0:1]
	v_mov_b64_e32 v[134:135], v[0:1]
	v_mov_b64_e32 v[152:153], v[0:1]
	v_mov_b64_e32 v[154:155], v[0:1]
	v_mov_b64_e32 v[156:157], v[0:1]
	v_mov_b64_e32 v[158:159], v[0:1]

.LBB0_1545:
	s_add_u32 s66, s26, 0x80
	s_addc_u32 s67, s27, 0
	s_add_u32 s68, s30, 0x100
	v_mov_b32_e32 v0, 0
	s_waitcnt vmcnt(0)
	v_lshl_add_u64 v[56:57], s[4:5], 0, v[170:171]
	v_lshl_add_u64 v[58:59], s[4:5], 0, v[172:173]
	s_addc_u32 s69, s31, 0
	s_mov_b32 s70, -2
	s_mov_b64 s[0:1], 0
	v_mov_b32_e32 v1, v0
	v_mov_b64_e32 v[2:3], v[0:1]
	v_mov_b64_e32 v[4:5], v[0:1]
	v_mov_b64_e32 v[6:7], v[0:1]
	v_mov_b64_e32 v[16:17], v[0:1]
	v_mov_b64_e32 v[18:19], v[0:1]
	v_mov_b64_e32 v[20:21], v[0:1]
	v_mov_b64_e32 v[22:23], v[0:1]
	v_mov_b64_e32 v[32:33], v[0:1]
	v_mov_b64_e32 v[34:35], v[0:1]
	v_mov_b64_e32 v[36:37], v[0:1]
	v_mov_b64_e32 v[38:39], v[0:1]
	v_mov_b64_e32 v[48:49], v[0:1]
	v_mov_b64_e32 v[50:51], v[0:1]
	v_mov_b64_e32 v[52:53], v[0:1]
	v_mov_b64_e32 v[54:55], v[0:1]
	v_mov_b64_e32 v[8:9], v[0:1]
	v_mov_b64_e32 v[10:11], v[0:1]
	v_mov_b64_e32 v[12:13], v[0:1]
	v_mov_b64_e32 v[14:15], v[0:1]
	v_mov_b64_e32 v[24:25], v[0:1]
	v_mov_b64_e32 v[26:27], v[0:1]
	v_mov_b64_e32 v[28:29], v[0:1]
	v_mov_b64_e32 v[30:31], v[0:1]
	v_mov_b64_e32 v[40:41], v[0:1]
	v_mov_b64_e32 v[42:43], v[0:1]
	v_mov_b64_e32 v[44:45], v[0:1]
	v_mov_b64_e32 v[46:47], v[0:1]
	s_waitcnt vmcnt(0)
	v_mov_b64_e32 v[64:65], v[0:1]
	v_mov_b64_e32 v[66:67], v[0:1]
	v_mov_b64_e32 v[68:69], v[0:1]
	v_mov_b64_e32 v[70:71], v[0:1]
	v_mov_b64_e32 v[80:81], v[0:1]
	v_mov_b64_e32 v[82:83], v[0:1]
	v_mov_b64_e32 v[84:85], v[0:1]
	v_mov_b64_e32 v[86:87], v[0:1]
	v_mov_b64_e32 v[104:105], v[0:1]
	v_mov_b64_e32 v[106:107], v[0:1]
	v_mov_b64_e32 v[108:109], v[0:1]
	v_mov_b64_e32 v[110:111], v[0:1]
	v_mov_b64_e32 v[128:129], v[0:1]
	v_mov_b64_e32 v[130:131], v[0:1]
	v_mov_b64_e32 v[132:133], v[0:1]
	v_mov_b64_e32 v[134:135], v[0:1]
	v_mov_b64_e32 v[144:145], v[0:1]
	v_mov_b64_e32 v[146:147], v[0:1]
	v_mov_b64_e32 v[148:149], v[0:1]
	v_mov_b64_e32 v[150:151], v[0:1]
	v_mov_b64_e32 v[92:93], v[0:1]
	v_mov_b64_e32 v[94:95], v[0:1]
	v_mov_b64_e32 v[96:97], v[0:1]
	v_mov_b64_e32 v[98:99], v[0:1]
	v_mov_b64_e32 v[120:121], v[0:1]
	v_mov_b64_e32 v[122:123], v[0:1]
	v_mov_b64_e32 v[124:125], v[0:1]
	v_mov_b64_e32 v[126:127], v[0:1]
	v_mov_b64_e32 v[136:137], v[0:1]
	v_mov_b64_e32 v[138:139], v[0:1]
	v_mov_b64_e32 v[140:141], v[0:1]
	v_mov_b64_e32 v[142:143], v[0:1]
	v_mov_b64_e32 v[152:153], v[0:1]
	v_mov_b64_e32 v[154:155], v[0:1]
	v_mov_b64_e32 v[156:157], v[0:1]
	v_mov_b64_e32 v[158:159], v[0:1]

.LBB0_1692:
	s_ashr_i32 s19, s18, 31
	s_lshl_b64 s[20:21], s[18:19], 9
	s_add_u32 s20, s42, s20
	s_addc_u32 s21, s43, s21
	s_and_b64 s[22:23], s[2:3], exec
	s_cselect_b32 s19, s21, s5
	s_cselect_b32 s65, s20, s4
	s_ashr_i32 s17, s16, 31
	s_lshl_b64 s[22:23], s[16:17], 17
	s_add_u32 s22, s44, s22
	s_addc_u32 s23, s45, s23
	s_and_b64 s[24:25], s[2:3], exec
	s_cselect_b32 s17, s23, s1
	s_cselect_b32 s66, s22, s0
	s_add_u32 s67, s65, 0x80
	v_mov_b32_e32 v0, 0
	s_addc_u32 s68, s19, 0
	s_mov_b64 s[28:29], 0
	s_mov_b64 s[24:25], -1
	s_mov_b64 s[26:27], 0
	v_mov_b32_e32 v1, v0
	v_mov_b64_e32 v[2:3], v[0:1]
	v_mov_b64_e32 v[4:5], v[0:1]
	v_mov_b64_e32 v[6:7], v[0:1]
	v_mov_b64_e32 v[16:17], v[0:1]
	v_mov_b64_e32 v[18:19], v[0:1]
	v_mov_b64_e32 v[20:21], v[0:1]
	v_mov_b64_e32 v[22:23], v[0:1]
	v_mov_b64_e32 v[32:33], v[0:1]
	v_mov_b64_e32 v[34:35], v[0:1]
	v_mov_b64_e32 v[36:37], v[0:1]
	v_mov_b64_e32 v[38:39], v[0:1]
	v_mov_b64_e32 v[48:49], v[0:1]
	v_mov_b64_e32 v[50:51], v[0:1]
	v_mov_b64_e32 v[52:53], v[0:1]
	v_mov_b64_e32 v[54:55], v[0:1]
	v_mov_b64_e32 v[8:9], v[0:1]
	v_mov_b64_e32 v[10:11], v[0:1]
	v_mov_b64_e32 v[12:13], v[0:1]
	v_mov_b64_e32 v[14:15], v[0:1]
	v_mov_b64_e32 v[24:25], v[0:1]
	v_mov_b64_e32 v[26:27], v[0:1]
	v_mov_b64_e32 v[28:29], v[0:1]
	v_mov_b64_e32 v[30:31], v[0:1]
	v_mov_b64_e32 v[40:41], v[0:1]
	v_mov_b64_e32 v[42:43], v[0:1]
	v_mov_b64_e32 v[44:45], v[0:1]
	v_mov_b64_e32 v[46:47], v[0:1]
	v_mov_b64_e32 v[56:57], v[0:1]
	v_mov_b64_e32 v[58:59], v[0:1]
	v_mov_b64_e32 v[60:61], v[0:1]
	v_mov_b64_e32 v[62:63], v[0:1]
	v_mov_b64_e32 v[64:65], v[0:1]
	v_mov_b64_e32 v[66:67], v[0:1]
	v_mov_b64_e32 v[68:69], v[0:1]
	v_mov_b64_e32 v[70:71], v[0:1]
	v_mov_b64_e32 v[80:81], v[0:1]
	v_mov_b64_e32 v[82:83], v[0:1]
	v_mov_b64_e32 v[84:85], v[0:1]
	v_mov_b64_e32 v[86:87], v[0:1]
	v_mov_b64_e32 v[96:97], v[0:1]
	v_mov_b64_e32 v[98:99], v[0:1]
	v_mov_b64_e32 v[100:101], v[0:1]
	v_mov_b64_e32 v[102:103], v[0:1]
	v_mov_b64_e32 v[104:105], v[0:1]
	v_mov_b64_e32 v[106:107], v[0:1]
	v_mov_b64_e32 v[112:113], v[0:1]
	v_mov_b64_e32 v[114:115], v[0:1]
	v_mov_b64_e32 v[72:73], v[0:1]
	v_mov_b64_e32 v[74:75], v[0:1]
	v_mov_b64_e32 v[76:77], v[0:1]
	v_mov_b64_e32 v[78:79], v[0:1]
	v_mov_b64_e32 v[88:89], v[0:1]
	v_mov_b64_e32 v[90:91], v[0:1]
	v_mov_b64_e32 v[92:93], v[0:1]
	v_mov_b64_e32 v[94:95], v[0:1]
	v_mov_b64_e32 v[108:109], v[0:1]
	v_mov_b64_e32 v[110:111], v[0:1]
	v_mov_b64_e32 v[116:117], v[0:1]
	v_mov_b64_e32 v[118:119], v[0:1]
	v_mov_b64_e32 v[120:121], v[0:1]
	v_mov_b64_e32 v[122:123], v[0:1]
	v_mov_b64_e32 v[124:125], v[0:1]
	v_mov_b64_e32 v[126:127], v[0:1]

.LBB0_2143:
	s_ashr_i32 s15, s14, 31
	s_lshl_b64 s[18:19], s[14:15], 20
	s_add_u32 s18, s30, s18
	s_addc_u32 s19, s31, s19
	s_and_b64 s[6:7], s[6:7], exec
	s_cselect_b32 s15, s19, s23
	s_cselect_b32 s48, s18, s22
	s_add_u32 s6, s24, 0xc0080
	s_addc_u32 s7, s25, 0
	s_add_u32 s49, s22, 0x100
	v_mov_b32_e32 v0, 0
	s_addc_u32 s50, s23, 0
	s_mov_b32 s51, -2
	s_waitcnt lgkmcnt(0)
	v_mov_b32_e32 v1, v0
	v_mov_b64_e32 v[2:3], v[0:1]
	v_mov_b64_e32 v[4:5], v[0:1]
	v_mov_b64_e32 v[6:7], v[0:1]
	v_mov_b64_e32 v[16:17], v[0:1]
	v_mov_b64_e32 v[18:19], v[0:1]
	v_mov_b64_e32 v[20:21], v[0:1]
	v_mov_b64_e32 v[22:23], v[0:1]
	v_mov_b64_e32 v[32:33], v[0:1]
	v_mov_b64_e32 v[34:35], v[0:1]
	v_mov_b64_e32 v[36:37], v[0:1]
	v_mov_b64_e32 v[38:39], v[0:1]
	v_mov_b64_e32 v[48:49], v[0:1]
	v_mov_b64_e32 v[50:51], v[0:1]
	v_mov_b64_e32 v[52:53], v[0:1]
	v_mov_b64_e32 v[54:55], v[0:1]
	v_mov_b64_e32 v[8:9], v[0:1]
	v_mov_b64_e32 v[10:11], v[0:1]
	v_mov_b64_e32 v[12:13], v[0:1]
	v_mov_b64_e32 v[14:15], v[0:1]
	v_mov_b64_e32 v[24:25], v[0:1]
	v_mov_b64_e32 v[26:27], v[0:1]
	v_mov_b64_e32 v[28:29], v[0:1]
	v_mov_b64_e32 v[30:31], v[0:1]
	v_mov_b64_e32 v[40:41], v[0:1]
	v_mov_b64_e32 v[42:43], v[0:1]
	v_mov_b64_e32 v[44:45], v[0:1]
	v_mov_b64_e32 v[46:47], v[0:1]
	s_waitcnt vmcnt(0)
	v_mov_b64_e32 v[56:57], v[0:1]
	v_mov_b64_e32 v[58:59], v[0:1]
	v_mov_b64_e32 v[60:61], v[0:1]
	v_mov_b64_e32 v[62:63], v[0:1]
	v_mov_b64_e32 v[64:65], v[0:1]
	v_mov_b64_e32 v[66:67], v[0:1]
	v_mov_b64_e32 v[68:69], v[0:1]
	v_mov_b64_e32 v[70:71], v[0:1]
	v_mov_b64_e32 v[80:81], v[0:1]
	v_mov_b64_e32 v[82:83], v[0:1]
	v_mov_b64_e32 v[84:85], v[0:1]
	v_mov_b64_e32 v[86:87], v[0:1]
	v_mov_b64_e32 v[96:97], v[0:1]
	v_mov_b64_e32 v[98:99], v[0:1]
	v_mov_b64_e32 v[100:101], v[0:1]
	v_mov_b64_e32 v[102:103], v[0:1]
	v_mov_b64_e32 v[112:113], v[0:1]
	v_mov_b64_e32 v[114:115], v[0:1]
	v_mov_b64_e32 v[116:117], v[0:1]
	v_mov_b64_e32 v[118:119], v[0:1]
	v_mov_b64_e32 v[72:73], v[0:1]
	v_mov_b64_e32 v[74:75], v[0:1]
	v_mov_b64_e32 v[76:77], v[0:1]
	v_mov_b64_e32 v[78:79], v[0:1]
	v_mov_b64_e32 v[88:89], v[0:1]
	v_mov_b64_e32 v[90:91], v[0:1]
	v_mov_b64_e32 v[92:93], v[0:1]
	v_mov_b64_e32 v[94:95], v[0:1]
	v_mov_b64_e32 v[104:105], v[0:1]
	v_mov_b64_e32 v[106:107], v[0:1]
	v_mov_b64_e32 v[108:109], v[0:1]
	v_mov_b64_e32 v[110:111], v[0:1]
	v_mov_b64_e32 v[120:121], v[0:1]
	v_mov_b64_e32 v[122:123], v[0:1]
	v_mov_b64_e32 v[124:125], v[0:1]
	v_mov_b64_e32 v[126:127], v[0:1]

.LBB0_2232:
	s_ashr_i32 s63, s62, 31
	s_lshl_b64 s[16:17], s[62:63], 11
	s_add_u32 s66, s88, s16
	s_addc_u32 s67, s89, s17
	s_and_b64 s[16:17], s[64:65], exec
	s_cselect_b32 s13, s67, s1
	s_cselect_b32 s23, s66, s0
	s_ashr_i32 s61, s60, 31
	s_lshl_b64 s[16:17], s[60:61], 19
	s_add_u32 s68, s72, s16
	s_addc_u32 s69, s73, s17
	s_and_b64 s[16:17], s[64:65], exec
	s_cselect_b32 s24, s69, s15
	s_cselect_b32 s25, s68, s14
	s_add_u32 s26, s23, 0x80
	s_addc_u32 s27, s13, 0
	s_add_u32 s33, s14, 0x100
	v_mov_b32_e32 v36, 0
	v_lshl_add_u64 v[96:97], s[0:1], 0, v[186:187]
	v_lshl_add_u64 v[98:99], s[0:1], 0, v[188:189]
	s_addc_u32 s61, s15, 0
	s_mov_b32 s63, -2
	s_mov_b64 s[14:15], 0
	v_mov_b32_e32 v37, v36
	v_mov_b64_e32 v[38:39], v[36:37]
	v_mov_b64_e32 v[68:69], v[36:37]
	v_mov_b64_e32 v[70:71], v[36:37]
	v_mov_b64_e32 v[0:1], v[36:37]
	v_mov_b64_e32 v[2:3], v[36:37]
	s_waitcnt vmcnt(0)
	v_mov_b64_e32 v[56:57], v[36:37]
	v_mov_b64_e32 v[58:59], v[36:37]
	v_mov_b64_e32 v[8:9], v[36:37]
	v_mov_b64_e32 v[10:11], v[36:37]
	v_mov_b64_e32 v[64:65], v[36:37]
	v_mov_b64_e32 v[66:67], v[36:37]
	v_mov_b64_e32 v[16:17], v[36:37]
	v_mov_b64_e32 v[18:19], v[36:37]
	v_mov_b64_e32 v[80:81], v[36:37]
	v_mov_b64_e32 v[82:83], v[36:37]
	v_mov_b64_e32 v[40:41], v[36:37]
	v_mov_b64_e32 v[42:43], v[36:37]
	v_mov_b64_e32 v[72:73], v[36:37]
	v_mov_b64_e32 v[74:75], v[36:37]
	v_mov_b64_e32 v[4:5], v[36:37]
	v_mov_b64_e32 v[6:7], v[36:37]
	v_mov_b64_e32 v[60:61], v[36:37]
	v_mov_b64_e32 v[62:63], v[36:37]
	v_mov_b64_e32 v[12:13], v[36:37]
	v_mov_b64_e32 v[14:15], v[36:37]
	v_mov_b64_e32 v[76:77], v[36:37]
	v_mov_b64_e32 v[78:79], v[36:37]
	v_mov_b64_e32 v[20:21], v[36:37]
	v_mov_b64_e32 v[22:23], v[36:37]
	v_mov_b64_e32 v[84:85], v[36:37]
	v_mov_b64_e32 v[86:87], v[36:37]
	v_mov_b64_e32 v[112:113], v[36:37]
	v_mov_b64_e32 v[114:115], v[36:37]
	v_mov_b64_e32 v[116:117], v[36:37]
	v_mov_b64_e32 v[118:119], v[36:37]
	v_mov_b64_e32 v[24:25], v[36:37]
	v_mov_b64_e32 v[26:27], v[36:37]
	v_mov_b64_e32 v[88:89], v[36:37]
	v_mov_b64_e32 v[90:91], v[36:37]
	v_mov_b64_e32 v[32:33], v[36:37]
	v_mov_b64_e32 v[34:35], v[36:37]
	v_mov_b64_e32 v[104:105], v[36:37]
	v_mov_b64_e32 v[106:107], v[36:37]
	v_mov_b64_e32 v[48:49], v[36:37]
	v_mov_b64_e32 v[50:51], v[36:37]
	v_mov_b64_e32 v[144:145], v[36:37]
	v_mov_b64_e32 v[146:147], v[36:37]
	v_mov_b64_e32 v[120:121], v[36:37]
	v_mov_b64_e32 v[122:123], v[36:37]
	v_mov_b64_e32 v[124:125], v[36:37]
	v_mov_b64_e32 v[126:127], v[36:37]
	v_mov_b64_e32 v[28:29], v[36:37]
	v_mov_b64_e32 v[30:31], v[36:37]
	v_mov_b64_e32 v[92:93], v[36:37]
	v_mov_b64_e32 v[94:95], v[36:37]
	v_mov_b64_e32 v[44:45], v[36:37]
	v_mov_b64_e32 v[46:47], v[36:37]
	v_mov_b64_e32 v[108:109], v[36:37]
	v_mov_b64_e32 v[110:111], v[36:37]
	v_mov_b64_e32 v[52:53], v[36:37]
	v_mov_b64_e32 v[54:55], v[36:37]
	v_mov_b64_e32 v[148:149], v[36:37]
	v_mov_b64_e32 v[150:151], v[36:37]

.LBB0_2395:
	s_add_u32 s47, s4, 0x80
	s_addc_u32 s48, s5, 0
	s_add_u32 s49, s16, 0x100
	v_mov_b32_e32 v0, 0
	s_addc_u32 s50, s17, 0
	v_lshl_add_u64 v[140:141], s[14:15], 0, v[132:133]
	v_lshl_add_u64 v[142:143], s[14:15], 0, v[134:135]
	s_mov_b32 s51, -2
	s_mov_b64 s[16:17], 0
	v_mov_b32_e32 v1, v0
	v_mov_b64_e32 v[2:3], v[0:1]
	v_mov_b64_e32 v[4:5], v[0:1]
	v_mov_b64_e32 v[6:7], v[0:1]
	v_mov_b64_e32 v[8:9], v[0:1]
	v_mov_b64_e32 v[10:11], v[0:1]
	v_mov_b64_e32 v[16:17], v[0:1]
	v_mov_b64_e32 v[18:19], v[0:1]
	v_mov_b64_e32 v[24:25], v[0:1]
	v_mov_b64_e32 v[26:27], v[0:1]
	v_mov_b64_e32 v[32:33], v[0:1]
	v_mov_b64_e32 v[34:35], v[0:1]
	v_mov_b64_e32 v[40:41], v[0:1]
	v_mov_b64_e32 v[42:43], v[0:1]
	v_mov_b64_e32 v[48:49], v[0:1]
	v_mov_b64_e32 v[50:51], v[0:1]
	v_mov_b64_e32 v[12:13], v[0:1]
	v_mov_b64_e32 v[14:15], v[0:1]
	v_mov_b64_e32 v[20:21], v[0:1]
	v_mov_b64_e32 v[22:23], v[0:1]
	v_mov_b64_e32 v[28:29], v[0:1]
	v_mov_b64_e32 v[30:31], v[0:1]
	v_mov_b64_e32 v[36:37], v[0:1]
	v_mov_b64_e32 v[38:39], v[0:1]
	v_mov_b64_e32 v[44:45], v[0:1]
	v_mov_b64_e32 v[46:47], v[0:1]
	v_mov_b64_e32 v[52:53], v[0:1]
	v_mov_b64_e32 v[54:55], v[0:1]
	v_mov_b64_e32 v[56:57], v[0:1]
	v_mov_b64_e32 v[58:59], v[0:1]
	v_mov_b64_e32 v[60:61], v[0:1]
	v_mov_b64_e32 v[62:63], v[0:1]
	v_mov_b64_e32 v[64:65], v[0:1]
	v_mov_b64_e32 v[66:67], v[0:1]
	v_mov_b64_e32 v[68:69], v[0:1]
	v_mov_b64_e32 v[70:71], v[0:1]
	v_mov_b64_e32 v[72:73], v[0:1]
	v_mov_b64_e32 v[74:75], v[0:1]
	v_mov_b64_e32 v[76:77], v[0:1]
	v_mov_b64_e32 v[78:79], v[0:1]
	v_mov_b64_e32 v[84:85], v[0:1]
	v_mov_b64_e32 v[86:87], v[0:1]
	v_mov_b64_e32 v[92:93], v[0:1]
	v_mov_b64_e32 v[94:95], v[0:1]
	v_mov_b64_e32 v[100:101], v[0:1]
	v_mov_b64_e32 v[102:103], v[0:1]
	v_mov_b64_e32 v[108:109], v[0:1]
	v_mov_b64_e32 v[110:111], v[0:1]
	v_mov_b64_e32 v[80:81], v[0:1]
	v_mov_b64_e32 v[82:83], v[0:1]
	v_mov_b64_e32 v[88:89], v[0:1]
	v_mov_b64_e32 v[90:91], v[0:1]
	v_mov_b64_e32 v[96:97], v[0:1]
	v_mov_b64_e32 v[98:99], v[0:1]
	v_mov_b64_e32 v[104:105], v[0:1]
	v_mov_b64_e32 v[106:107], v[0:1]
	v_mov_b64_e32 v[112:113], v[0:1]
	v_mov_b64_e32 v[114:115], v[0:1]
	v_mov_b64_e32 v[116:117], v[0:1]
	v_mov_b64_e32 v[118:119], v[0:1]
	v_mov_b64_e32 v[120:121], v[0:1]
	v_mov_b64_e32 v[122:123], v[0:1]
	v_mov_b64_e32 v[124:125], v[0:1]
	v_mov_b64_e32 v[126:127], v[0:1]
